# hand-written software-pipelined dense GQA attention item (same numerics)
# speedup vs baseline: 1.0398x; 1.0398x over previous
; DI int get_tid() { int t = threadIdx.x; asm volatile("" : "+v"(t)); return t; }
; template <bool NA, bool TRACK>
; DI void attn_item(char* lds, const bf16_t* P, bf16_t* Y, const bf16_t* vt, int rp, int q_off, int k1_off, int nt1,
;                   int vk1, int k2_off, int nt2, int vk2, int g_off, int y_off, int rlo, const float* rpb) {
;   asm volatile("" : "+v"(q_off), "+v"(g_off), "+v"(y_off));
;   const bf16_t* qp = P + q_off;
;   const bf16_t* kp1 = P + k1_off;
;   const bf16_t* kp2 = P + k2_off;
;   const int tid = get_tid(), lane = tid & 63, w = tid >> 6, r = lane & 31, h = lane >> 5;
;   const int lr = tid >> 3, lc = tid & 7;
;   const int nt = nt1 + nt2;
;   const int woff = lr * 128 + ((lc ^ ((lr >> 1) & 7)) << 4);
;   const int swz = (r >> 1) & 7;
;   float* tab = (float*)(lds + 131072);
;   int rw = 0, r0w = 0, cq = 0, c0 = 0;
;   if (NA) {
;     rw = rp * 4 + (w >> 1);
;     r0w = clampi(rw - 4, 0, 24);
;     cq = (w & 1) * 32 + r;
;     c0 = clampi(cq - 8, 0, 48);
;     for (int e = tid; e < 15 * 128; e += NTHREADS) {
;       const int dr = e >> 7, dc = (e & 127) - 48;
;       tab[e] = (dc >= 0 && dc < 31) ? rpb[dr * 31 + dc] * LOG2E : 0.f;
;     }
;   }
;   bf16x8 qf[4];
; #pragma unroll
;   for (int ks = 0; ks < 4; ++ks) qf[ks] = *(const bf16x8*)(qp + (size_t)(w * 32 + r) * INW + ks * 16 + h * 8);
;   u32x2 gate[2][4];
; #pragma unroll
;   for (int dm = 0; dm < 2; ++dm)
; #pragma unroll
;     for (int g = 0; g < 4; ++g)
;       gate[dm][g] = *(const u32x2*)(P + g_off + (size_t)(w * 32 + r) * INW + dm * 32 + 8 * g + 4 * h);
; #pragma unroll
;   for (int ks = 0; ks < 4; ++ks) asm volatile("" : "+v"(qf[ks]));
; #pragma unroll
;   for (int dm = 0; dm < 2; ++dm)
; #pragma unroll
;     for (int g = 0; g < 4; ++g) asm volatile("" : "+v"(gate[dm][g]));
;   f32x16 o[2];
;   o[0] = zero16(); o[1] = zero16();
;   f32x16 negm;
; #pragma unroll
;   for (int i = 0; i < 16; ++i) negm[i] = 0.f;
;   float l_run = 0.f;
;   constexpr int TPI = 4;
;   const int niter = (nt + TPI - 1) / TPI;
;   u32x4 rk[TPI], rv[TPI];
;     ...
;   ATT_LOAD(0);
;   ATT_WRITE(0, 0);
;   __syncthreads();
.LBB0_109:
	s_lshl_b32 s3, s25, 6
	s_add_i32 s12, s3, 0x700
	s_and_b64 s[8:9], s[4:5], exec
	s_cselect_b32 s26, s12, s3
	s_lshl_b32 s10, s10, 6
	s_and_b64 s[8:9], s[4:5], exec
	s_movk_i32 s8, 0x800
	s_cselect_b32 s8, s8, 0x200
	s_add_i32 s13, s8, s10
	s_add_i32 s8, s3, 0xa00
	s_add_i32 s9, s3, 0x300
	s_and_b64 s[4:5], s[4:5], exec
	v_readlane_b32 s36, v254, 41
	s_cselect_b32 s28, s9, s3
	s_cselect_b32 s3, 8, 7
	v_readlane_b32 s46, v254, 51
	v_readlane_b32 s47, v254, 52
	v_readlane_b32 s48, v254, 53
	v_readlane_b32 s49, v254, 54
	s_cselect_b32 s27, s8, s9
	s_cselect_b32 s4, s49, s47
	s_cselect_b32 s5, s48, s46
	s_lshl_b32 s3, s0, s3
	s_add_i32 s3, s3, s10
	s_mul_hi_i32 s9, s3, 0x1200
	s_mulk_i32 s3, 0x1200
	s_add_u32 s8, s5, s3
	s_mul_i32 s0, s0, 0xb0000
	s_addc_u32 s9, s4, s9
	s_add_i32 s0, s0, s13
	s_mul_i32 s3, s11, 0xb00
	s_mulk_i32 s2, 0xb00
	s_add_i32 s10, s0, 0x5800000
	s_lshl_b32 s0, s11, 10
	s_add_i32 s26, s26, s3
	s_add_i32 s12, s13, s2
	s_add_i32 s27, s27, s3
	s_add_i32 s28, s28, s0
	s_andn2_b64 vcc, exec, s[6:7]
	s_mov_b64 s[2:3], -1
	v_readlane_b32 s37, v254, 42
	v_readlane_b32 s38, v254, 43
	v_readlane_b32 s39, v254, 44
	v_readlane_b32 s40, v254, 45
	v_readlane_b32 s41, v254, 46
	v_readlane_b32 s42, v254, 47
	v_readlane_b32 s43, v254, 48
	v_readlane_b32 s44, v254, 49
	v_readlane_b32 s45, v254, 50
	v_readlane_b32 s50, v254, 55
	v_readlane_b32 s51, v254, 56
	s_cbranch_vccz .LBB0_184
	v_readlane_b32 s4, v255, 10
	v_readlane_b32 s5, v255, 11
	s_ashr_i32 s13, s12, 31
	s_ashr_i32 s11, s10, 31
	s_and_b64 vcc, exec, s[4:5]
	s_cbranch_vccz .LBB0_156
	v_readlane_b32 s44, v254, 49
	v_readlane_b32 s45, v254, 50
	s_mov_b32 s34, s26
	s_ashr_i32 s35, s26, 31
	s_lshl_b64 s[34:35], s[34:35], 1
	s_add_u32 s34, s34, s44
	s_addc_u32 s35, s35, s45
	s_mov_b32 s36, s27
	s_ashr_i32 s37, s27, 31
	s_lshl_b64 s[36:37], s[36:37], 1
	s_add_u32 s36, s36, s44
	s_addc_u32 s37, s37, s45
	s_lshl_b64 s[4:5], s[12:13], 1
	s_add_u32 s4, s4, s44
	s_addc_u32 s5, s5, s45
	s_lshl_b64 s[6:7], s[10:11], 1
	s_add_u32 s6, s6, s44
	s_addc_u32 s7, s7, s45
	s_add_i32 s19, s79, 4
	s_lshr_b32 s19, s19, 2
	s_mov_b32 s18, 0
	v_bfe_u32 v147, v251, 5, 1
	v_ashrrev_i32_e32 v0, 1, v251
	s_movk_i32 s0, 0xffe0
	v_bfi_b32 v146, s0, v0, v251
	v_lshlrev_b32_e32 v138, 3, v147
	v_mov_b32_e32 v150, s28
	v_mul_u32_u24_e32 v0, 0x1600, v146
	v_lshl_add_u32 v188, v147, 4, v0
	v_lshl_add_u32 v189, v147, 3, v0
	v_lshrrev_b32_e32 v0, 3, v251
	v_and_b32_e32 v191, 7, v251
	v_mul_u32_u24_e32 v228, 0x1600, v0
	v_lshl_add_u32 v228, v191, 4, v228
	v_mul_u32_u24_e32 v229, 0x1200, v0
	v_lshl_add_u32 v229, v191, 4, v229
	global_load_dwordx4 v[98:101], v188, s[34:35]
	global_load_dwordx4 v[102:105], v188, s[34:35] offset:32
	global_load_dwordx4 v[106:109], v188, s[34:35] offset:64
	global_load_dwordx4 v[110:113], v188, s[34:35] offset:96
	s_mov_b32 s20, 0
	s_lshl_b32 s20, s20, 2
	s_cmp_lt_i32 s20, s79
	s_cselect_b32 s21, 0, s79
	s_cselect_b32 s22, s4, s6
	s_cselect_b32 s23, s5, s7
	s_cselect_b32 s29, s90, 0x800
	s_sub_i32 s20, s20, s21
	s_mul_i32 s21, s20, 0x58000
	s_add_u32 s14, s22, s21
	s_addc_u32 s15, s23, 0
	s_lshl_b32 s20, s20, 6
	s_add_i32 s20, s20, s29
	s_lshl_b32 s20, s20, 1
	s_add_u32 s16, s8, s20
	s_addc_u32 s17, s9, 0
	global_load_dwordx4 v[192:195], v228, s[14:15]
	s_add_u32 s14, s14, 0x58000
	s_addc_u32 s15, s15, 0
	global_load_dwordx4 v[196:199], v229, s[16:17]
	global_load_dwordx4 v[200:203], v228, s[14:15]
	s_add_u32 s14, s14, 0x58000
	s_addc_u32 s15, s15, 0
	global_load_dwordx4 v[204:207], v229, s[16:17] offset:128
	global_load_dwordx4 v[208:211], v228, s[14:15]
	s_add_u32 s14, s14, 0x58000
	s_addc_u32 s15, s15, 0
	global_load_dwordx4 v[212:215], v229, s[16:17] offset:256
	global_load_dwordx4 v[216:219], v228, s[14:15]
	global_load_dwordx4 v[220:223], v229, s[16:17] offset:384
	global_load_dwordx2 v[148:149], v189, s[36:37]
	global_load_dwordx2 v[144:145], v189, s[36:37] offset:16
	global_load_dwordx2 v[142:143], v189, s[36:37] offset:32
	global_load_dwordx2 v[140:141], v189, s[36:37] offset:48
	global_load_dwordx2 v[136:137], v189, s[36:37] offset:64
	global_load_dwordx2 v[134:135], v189, s[36:37] offset:80
	global_load_dwordx2 v[132:133], v189, s[36:37] offset:96
	global_load_dwordx2 v[130:131], v189, s[36:37] offset:112
	v_lshlrev_b32_e32 v191, 4, v251
	v_xor_b32_e32 v191, v191, v251
	v_and_b32_e32 v191, 0x70, v191
	v_lshl_or_b32 v139, v0, 7, v191
	v_and_b32_e32 v0, 31, v251
	v_lshlrev_b32_e32 v0, 7, v0
	v_bfe_u32 v191, v251, 1, 3
	v_xor_b32_e32 v191, v191, v147
	v_lshl_or_b32 v224, v191, 4, v0
	v_xor_b32_e32 v232, 2, v191
	v_lshl_or_b32 v225, v232, 4, v0
	v_xor_b32_e32 v232, 4, v191
	v_lshl_or_b32 v226, v232, 4, v0
	v_xor_b32_e32 v232, 6, v191
	v_lshl_or_b32 v227, v232, 4, v0
	v_mov_b32_e32 v2, 0
	v_mov_b32_e32 v3, 0
	v_mov_b32_e32 v4, 0
	v_mov_b32_e32 v5, 0
	v_mov_b32_e32 v6, 0
	v_mov_b32_e32 v7, 0
	v_mov_b32_e32 v8, 0
	v_mov_b32_e32 v9, 0
	v_mov_b32_e32 v10, 0
	v_mov_b32_e32 v11, 0
	v_mov_b32_e32 v12, 0
	v_mov_b32_e32 v13, 0
	v_mov_b32_e32 v14, 0
	v_mov_b32_e32 v15, 0
	v_mov_b32_e32 v16, 0
	v_mov_b32_e32 v17, 0
	v_mov_b32_e32 v18, 0
	v_mov_b32_e32 v19, 0
	v_mov_b32_e32 v20, 0
	v_mov_b32_e32 v21, 0
	v_mov_b32_e32 v22, 0
	v_mov_b32_e32 v23, 0
	v_mov_b32_e32 v24, 0
	v_mov_b32_e32 v25, 0
	v_mov_b32_e32 v26, 0
	v_mov_b32_e32 v27, 0
	v_mov_b32_e32 v28, 0
	v_mov_b32_e32 v29, 0
	v_mov_b32_e32 v30, 0
	v_mov_b32_e32 v31, 0
	v_mov_b32_e32 v32, 0
	v_mov_b32_e32 v33, 0
	v_mov_b32_e32 v184, 0
	v_mov_b32_e32 v185, 0
	v_mov_b32_e32 v186, 0
	v_mov_b32_e32 v187, 0
	s_waitcnt vmcnt(0)
	ds_write_b128 v139, v[192:195]
	ds_write_b128 v139, v[196:199] offset:8192
	ds_write_b128 v139, v[200:203] offset:16384
	ds_write_b128 v139, v[204:207] offset:24576
	ds_write_b128 v139, v[208:211] offset:32768
	ds_write_b128 v139, v[212:215] offset:40960
	ds_write_b128 v139, v[216:219] offset:49152
	ds_write_b128 v139, v[220:223] offset:57344
	v_xor_b32_e32 v139, 0x10000, v139
	s_waitcnt lgkmcnt(0)
	s_barrier
; DI f32x16 mfma32(bf16x8 a, bf16x8 b, f32x16 c) { return __builtin_amdgcn_mfma_f32_32x32x16_bf16(a, b, c, 0, 0, 0); }
; DI float fast_exp2(float x) { return __builtin_amdgcn_exp2f(x); }
; template <bool NA, bool TRACK>
; DI void attn_item(char* lds, const bf16_t* P, bf16_t* Y, const bf16_t* vt, int rp, int q_off, int k1_off, int nt1,
;                   int vk1, int k2_off, int nt2, int vk2, int g_off, int y_off, int rlo, const float* rpb) {
;     ...
;       ATT_QK(sc, 0);
; #pragma unroll
;       for (int j = 0; j < TPI; ++j) {
;         const char* Vs = Kb + j * 16384 + 8192;
;         if (j + 1 < TPI) ATT_QK(sn, j + 1);
;         float ps = 0.f;
; #pragma unroll
;         for (int kt = 0; kt < 2; ++kt) {
;           bf16x8 vf[4];
; #pragma unroll
;           for (int sp = 0; sp < 2; ++sp)
; #pragma unroll
;             for (int dm = 0; dm < 2; ++dm)
;               vf[sp * 2 + dm] = *(const bf16x8*)(Vs + (dm * 32 + r) * 128 + (((4 * kt + 2 * sp + h) ^ swz) << 4));
; #pragma unroll
;           for (int i = 0; i < 16; ++i) {
;             const float pv = fast_exp2(sc[kt][i]);
;             ps += pv;
;             sc[kt][i] = pv;
;           }
; #pragma unroll
;           for (int sp = 0; sp < 2; ++sp) {
;             u32x4 pu;
;             pu[0] = pk2(sc[kt][8 * sp + 0], sc[kt][8 * sp + 1]);
;             pu[1] = pk2(sc[kt][8 * sp + 2], sc[kt][8 * sp + 3]);
;             pu[2] = pk2(sc[kt][8 * sp + 4], sc[kt][8 * sp + 5]);
;             pu[3] = pk2(sc[kt][8 * sp + 6], sc[kt][8 * sp + 7]);
;             const bf16x8 pf = __builtin_bit_cast(bf16x8, pu);
; #pragma unroll
;             for (int dm = 0; dm < 2; ++dm) o[dm] = mfma32(vf[sp * 2 + dm], pf, o[dm]);
;           }
;         }
.Ldn_loop:
	ds_read_b128 v[114:117], v224
	ds_read_b128 v[118:121], v225
	ds_read_b128 v[122:125], v226
	ds_read_b128 v[126:129], v227
	ds_read_b128 v[152:155], v224 offset:4096
	ds_read_b128 v[156:159], v225 offset:4096
	ds_read_b128 v[160:163], v226 offset:4096
	ds_read_b128 v[164:167], v227 offset:4096
	s_add_i32 s20, s18, 1
	s_cmp_ge_i32 s20, s19
	s_cbranch_scc1 .Ldn_skipld_loop
	s_lshl_b32 s20, s20, 2
	s_cmp_lt_i32 s20, s79
	s_cselect_b32 s21, 0, s79
	s_cselect_b32 s22, s4, s6
	s_cselect_b32 s23, s5, s7
	s_cselect_b32 s29, s90, 0x800
	s_sub_i32 s20, s20, s21
	s_mul_i32 s21, s20, 0x58000
	s_add_u32 s14, s22, s21
	s_addc_u32 s15, s23, 0
	s_lshl_b32 s20, s20, 6
	s_add_i32 s20, s20, s29
	s_lshl_b32 s20, s20, 1
	s_add_u32 s16, s8, s20
	s_addc_u32 s17, s9, 0
	global_load_dwordx4 v[192:195], v228, s[14:15]
	s_add_u32 s14, s14, 0x58000
	s_addc_u32 s15, s15, 0
	global_load_dwordx4 v[196:199], v229, s[16:17]
	global_load_dwordx4 v[200:203], v228, s[14:15]
	s_add_u32 s14, s14, 0x58000
	s_addc_u32 s15, s15, 0
	global_load_dwordx4 v[204:207], v229, s[16:17] offset:128
	global_load_dwordx4 v[208:211], v228, s[14:15]
	s_add_u32 s14, s14, 0x58000
	s_addc_u32 s15, s15, 0
	global_load_dwordx4 v[212:215], v229, s[16:17] offset:256
	global_load_dwordx4 v[216:219], v228, s[14:15]
	global_load_dwordx4 v[220:223], v229, s[16:17] offset:384
.Ldn_skipld_loop:
	s_waitcnt lgkmcnt(7)
	v_mfma_f32_32x32x16_bf16 v[34:49], v[114:117], v[98:101], 0
	ds_read_b128 v[114:117], v224 offset:16384
	s_waitcnt lgkmcnt(7)
	v_mfma_f32_32x32x16_bf16 v[34:49], v[118:121], v[102:105], v[34:49]
	ds_read_b128 v[118:121], v225 offset:16384
	s_waitcnt lgkmcnt(7)
	v_mfma_f32_32x32x16_bf16 v[34:49], v[122:125], v[106:109], v[34:49]
	ds_read_b128 v[122:125], v226 offset:16384
	s_waitcnt lgkmcnt(7)
	v_mfma_f32_32x32x16_bf16 v[34:49], v[126:129], v[110:113], v[34:49]
	ds_read_b128 v[126:129], v227 offset:16384
	s_waitcnt lgkmcnt(7)
	v_mfma_f32_32x32x16_bf16 v[50:65], v[152:155], v[98:101], 0
	ds_read_b128 v[152:155], v224 offset:8192
	s_waitcnt lgkmcnt(7)
	v_mfma_f32_32x32x16_bf16 v[50:65], v[156:159], v[102:105], v[50:65]
	ds_read_b128 v[156:159], v224 offset:12288
	s_waitcnt lgkmcnt(7)
	v_mfma_f32_32x32x16_bf16 v[50:65], v[160:163], v[106:109], v[50:65]
	ds_read_b128 v[160:163], v225 offset:8192
	s_waitcnt lgkmcnt(7)
	v_mfma_f32_32x32x16_bf16 v[50:65], v[164:167], v[110:113], v[50:65]
	ds_read_b128 v[164:167], v225 offset:12288
	s_nop 2
	v_exp_f32_e32 v34, v34
	v_exp_f32_e32 v35, v35
	v_exp_f32_e32 v36, v36
	v_exp_f32_e32 v37, v37
	v_cvt_pk_bf16_f32 v168, v34, v35
	v_add_f32_e32 v184, v184, v34
	v_add_f32_e32 v185, v185, v35
	v_exp_f32_e32 v38, v38
	v_exp_f32_e32 v39, v39
	v_cvt_pk_bf16_f32 v169, v36, v37
	v_add_f32_e32 v186, v186, v36
	v_add_f32_e32 v187, v187, v37
	v_exp_f32_e32 v40, v40
	v_exp_f32_e32 v41, v41
	v_add_f32_e32 v184, v184, v38
	v_add_f32_e32 v185, v185, v39
	v_cvt_pk_bf16_f32 v170, v38, v39
	v_add_f32_e32 v186, v186, v40
	v_add_f32_e32 v187, v187, v41
	v_cvt_pk_bf16_f32 v171, v40, v41
	s_waitcnt lgkmcnt(7)
	v_mfma_f32_32x32x16_bf16 v[66:81], v[114:117], v[98:101], 0
	ds_read_b128 v[114:117], v224 offset:20480
	v_exp_f32_e32 v42, v42
	v_exp_f32_e32 v43, v43
	v_exp_f32_e32 v44, v44
	s_waitcnt lgkmcnt(7)
	v_mfma_f32_32x32x16_bf16 v[66:81], v[118:121], v[102:105], v[66:81]
	ds_read_b128 v[118:121], v225 offset:20480
	v_exp_f32_e32 v45, v45
	v_cvt_pk_bf16_f32 v172, v42, v43
	v_add_f32_e32 v184, v184, v42
	v_add_f32_e32 v185, v185, v43
	v_exp_f32_e32 v46, v46
	s_waitcnt lgkmcnt(7)
	v_mfma_f32_32x32x16_bf16 v[66:81], v[122:125], v[106:109], v[66:81]
	ds_read_b128 v[122:125], v226 offset:20480
	v_exp_f32_e32 v47, v47
	v_cvt_pk_bf16_f32 v173, v44, v45
	v_add_f32_e32 v186, v186, v44
	v_add_f32_e32 v187, v187, v45
	v_exp_f32_e32 v48, v48
	s_waitcnt lgkmcnt(7)
	v_mfma_f32_32x32x16_bf16 v[66:81], v[126:129], v[110:113], v[66:81]
	ds_read_b128 v[126:129], v227 offset:20480
	v_exp_f32_e32 v49, v49
	v_add_f32_e32 v184, v184, v46
	v_add_f32_e32 v185, v185, v47
	v_cvt_pk_bf16_f32 v174, v46, v47
	v_add_f32_e32 v186, v186, v48
	v_add_f32_e32 v187, v187, v49
	v_cvt_pk_bf16_f32 v175, v48, v49
	s_waitcnt lgkmcnt(7)
	v_mfma_f32_32x32x16_bf16 v[18:33], v[152:155], v[168:171], v[18:33]
	ds_read_b128 v[152:155], v226 offset:8192
	v_exp_f32_e32 v50, v50
	v_exp_f32_e32 v51, v51
	v_exp_f32_e32 v52, v52
	s_waitcnt lgkmcnt(7)
	v_mfma_f32_32x32x16_bf16 v[2:17], v[156:159], v[168:171], v[2:17]
	ds_read_b128 v[156:159], v226 offset:12288
	v_exp_f32_e32 v53, v53
	v_cvt_pk_bf16_f32 v176, v50, v51
	v_add_f32_e32 v184, v184, v50
	v_add_f32_e32 v185, v185, v51
	v_exp_f32_e32 v54, v54
	s_waitcnt lgkmcnt(7)
	v_mfma_f32_32x32x16_bf16 v[18:33], v[160:163], v[172:175], v[18:33]
	ds_read_b128 v[160:163], v227 offset:8192
	v_exp_f32_e32 v55, v55
	v_cvt_pk_bf16_f32 v177, v52, v53
	v_add_f32_e32 v186, v186, v52
	v_add_f32_e32 v187, v187, v53
	v_exp_f32_e32 v56, v56
	s_waitcnt lgkmcnt(7)
	v_mfma_f32_32x32x16_bf16 v[2:17], v[164:167], v[172:175], v[2:17]
	ds_read_b128 v[164:167], v227 offset:12288
	v_exp_f32_e32 v57, v57
	v_add_f32_e32 v184, v184, v54
	v_add_f32_e32 v185, v185, v55
	v_cvt_pk_bf16_f32 v178, v54, v55
	v_add_f32_e32 v186, v186, v56
	v_add_f32_e32 v187, v187, v57
	v_cvt_pk_bf16_f32 v179, v56, v57
	s_waitcnt lgkmcnt(7)
	v_mfma_f32_32x32x16_bf16 v[82:97], v[114:117], v[98:101], 0
	ds_read_b128 v[114:117], v224 offset:32768
	v_exp_f32_e32 v58, v58
	v_exp_f32_e32 v59, v59
	v_exp_f32_e32 v60, v60
	s_waitcnt lgkmcnt(7)
	v_mfma_f32_32x32x16_bf16 v[82:97], v[118:121], v[102:105], v[82:97]
	ds_read_b128 v[118:121], v225 offset:32768
	v_exp_f32_e32 v61, v61
	v_cvt_pk_bf16_f32 v180, v58, v59
	v_add_f32_e32 v184, v184, v58
	v_add_f32_e32 v185, v185, v59
	v_exp_f32_e32 v62, v62
	s_waitcnt lgkmcnt(7)
; DI f32x16 mfma32(bf16x8 a, bf16x8 b, f32x16 c) { return __builtin_amdgcn_mfma_f32_32x32x16_bf16(a, b, c, 0, 0, 0); }
; DI float fast_exp2(float x) { return __builtin_amdgcn_exp2f(x); }
; template <bool NA, bool TRACK>
; DI void attn_item(char* lds, const bf16_t* P, bf16_t* Y, const bf16_t* vt, int rp, int q_off, int k1_off, int nt1,
;                   int vk1, int k2_off, int nt2, int vk2, int g_off, int y_off, int rlo, const float* rpb) {
;     ...
;       ATT_QK(sc, 0);
; #pragma unroll
;       for (int j = 0; j < TPI; ++j) {
;         const char* Vs = Kb + j * 16384 + 8192;
;         if (j + 1 < TPI) ATT_QK(sn, j + 1);
;         float ps = 0.f;
; #pragma unroll
;         for (int kt = 0; kt < 2; ++kt) {
;           bf16x8 vf[4];
; #pragma unroll
;           for (int sp = 0; sp < 2; ++sp)
; #pragma unroll
;             for (int dm = 0; dm < 2; ++dm)
;               vf[sp * 2 + dm] = *(const bf16x8*)(Vs + (dm * 32 + r) * 128 + (((4 * kt + 2 * sp + h) ^ swz) << 4));
; #pragma unroll
;           for (int i = 0; i < 16; ++i) {
;             const float pv = fast_exp2(sc[kt][i]);
;             ps += pv;
;             sc[kt][i] = pv;
;           }
; #pragma unroll
;           for (int sp = 0; sp < 2; ++sp) {
;             u32x4 pu;
;             pu[0] = pk2(sc[kt][8 * sp + 0], sc[kt][8 * sp + 1]);
;             pu[1] = pk2(sc[kt][8 * sp + 2], sc[kt][8 * sp + 3]);
;             pu[2] = pk2(sc[kt][8 * sp + 4], sc[kt][8 * sp + 5]);
;             pu[3] = pk2(sc[kt][8 * sp + 6], sc[kt][8 * sp + 7]);
;             const bf16x8 pf = __builtin_bit_cast(bf16x8, pu);
; #pragma unroll
;             for (int dm = 0; dm < 2; ++dm) o[dm] = mfma32(vf[sp * 2 + dm], pf, o[dm]);
;           }
;         }
	v_mfma_f32_32x32x16_bf16 v[82:97], v[122:125], v[106:109], v[82:97]
	ds_read_b128 v[122:125], v226 offset:32768
	v_exp_f32_e32 v63, v63
	v_cvt_pk_bf16_f32 v181, v60, v61
	v_add_f32_e32 v186, v186, v60
	v_add_f32_e32 v187, v187, v61
	v_exp_f32_e32 v64, v64
	s_waitcnt lgkmcnt(7)
	v_mfma_f32_32x32x16_bf16 v[82:97], v[126:129], v[110:113], v[82:97]
	ds_read_b128 v[126:129], v227 offset:32768
	v_exp_f32_e32 v65, v65
	v_add_f32_e32 v184, v184, v62
	v_add_f32_e32 v185, v185, v63
	v_cvt_pk_bf16_f32 v182, v62, v63
	v_add_f32_e32 v186, v186, v64
	v_add_f32_e32 v187, v187, v65
	v_cvt_pk_bf16_f32 v183, v64, v65
	s_waitcnt lgkmcnt(7)
	v_mfma_f32_32x32x16_bf16 v[18:33], v[152:155], v[176:179], v[18:33]
	ds_read_b128 v[152:155], v224 offset:24576
	v_exp_f32_e32 v66, v66
	v_exp_f32_e32 v67, v67
	v_exp_f32_e32 v68, v68
	s_waitcnt lgkmcnt(7)
	v_mfma_f32_32x32x16_bf16 v[2:17], v[156:159], v[176:179], v[2:17]
	ds_read_b128 v[156:159], v224 offset:28672
	v_exp_f32_e32 v69, v69
	v_cvt_pk_bf16_f32 v168, v66, v67
	v_add_f32_e32 v184, v184, v66
	v_add_f32_e32 v185, v185, v67
	v_exp_f32_e32 v70, v70
	s_waitcnt lgkmcnt(7)
	v_mfma_f32_32x32x16_bf16 v[18:33], v[160:163], v[180:183], v[18:33]
	ds_read_b128 v[160:163], v225 offset:24576
	v_exp_f32_e32 v71, v71
	v_cvt_pk_bf16_f32 v169, v68, v69
	v_add_f32_e32 v186, v186, v68
	v_add_f32_e32 v187, v187, v69
	v_exp_f32_e32 v72, v72
	s_waitcnt lgkmcnt(7)
	v_mfma_f32_32x32x16_bf16 v[2:17], v[164:167], v[180:183], v[2:17]
	ds_read_b128 v[164:167], v225 offset:28672
	v_exp_f32_e32 v73, v73
	v_add_f32_e32 v184, v184, v70
	v_add_f32_e32 v185, v185, v71
	v_cvt_pk_bf16_f32 v170, v70, v71
	v_add_f32_e32 v186, v186, v72
	v_add_f32_e32 v187, v187, v73
	v_cvt_pk_bf16_f32 v171, v72, v73
	s_waitcnt lgkmcnt(7)
	v_mfma_f32_32x32x16_bf16 v[34:49], v[114:117], v[98:101], 0
	ds_read_b128 v[114:117], v224 offset:36864
	v_exp_f32_e32 v74, v74
	v_exp_f32_e32 v75, v75
	v_exp_f32_e32 v76, v76
	s_waitcnt lgkmcnt(7)
	v_mfma_f32_32x32x16_bf16 v[34:49], v[118:121], v[102:105], v[34:49]
	ds_read_b128 v[118:121], v225 offset:36864
	v_exp_f32_e32 v77, v77
	v_cvt_pk_bf16_f32 v172, v74, v75
	v_add_f32_e32 v184, v184, v74
	v_add_f32_e32 v185, v185, v75
	v_exp_f32_e32 v78, v78
	s_waitcnt lgkmcnt(7)
	v_mfma_f32_32x32x16_bf16 v[34:49], v[122:125], v[106:109], v[34:49]
	ds_read_b128 v[122:125], v226 offset:36864
	v_exp_f32_e32 v79, v79
	v_cvt_pk_bf16_f32 v173, v76, v77
	v_add_f32_e32 v186, v186, v76
	v_add_f32_e32 v187, v187, v77
	v_exp_f32_e32 v80, v80
	s_waitcnt lgkmcnt(7)
	v_mfma_f32_32x32x16_bf16 v[34:49], v[126:129], v[110:113], v[34:49]
	ds_read_b128 v[126:129], v227 offset:36864
	v_exp_f32_e32 v81, v81
	v_add_f32_e32 v184, v184, v78
	v_add_f32_e32 v185, v185, v79
	v_cvt_pk_bf16_f32 v174, v78, v79
	v_add_f32_e32 v186, v186, v80
	v_add_f32_e32 v187, v187, v81
	v_cvt_pk_bf16_f32 v175, v80, v81
	s_waitcnt lgkmcnt(7)
	v_mfma_f32_32x32x16_bf16 v[18:33], v[152:155], v[168:171], v[18:33]
	ds_read_b128 v[152:155], v226 offset:24576
	v_exp_f32_e32 v82, v82
	v_exp_f32_e32 v83, v83
	v_exp_f32_e32 v84, v84
	s_waitcnt lgkmcnt(7)
	v_mfma_f32_32x32x16_bf16 v[2:17], v[156:159], v[168:171], v[2:17]
	ds_read_b128 v[156:159], v226 offset:28672
	v_exp_f32_e32 v85, v85
	v_cvt_pk_bf16_f32 v176, v82, v83
	v_add_f32_e32 v184, v184, v82
	v_add_f32_e32 v185, v185, v83
	v_exp_f32_e32 v86, v86
	s_waitcnt lgkmcnt(7)
	v_mfma_f32_32x32x16_bf16 v[18:33], v[160:163], v[172:175], v[18:33]
	ds_read_b128 v[160:163], v227 offset:24576
	v_exp_f32_e32 v87, v87
	v_cvt_pk_bf16_f32 v177, v84, v85
	v_add_f32_e32 v186, v186, v84
	v_add_f32_e32 v187, v187, v85
	v_exp_f32_e32 v88, v88
	s_waitcnt lgkmcnt(7)
	v_mfma_f32_32x32x16_bf16 v[2:17], v[164:167], v[172:175], v[2:17]
	ds_read_b128 v[164:167], v227 offset:28672
	v_exp_f32_e32 v89, v89
	v_add_f32_e32 v184, v184, v86
	v_add_f32_e32 v185, v185, v87
	v_cvt_pk_bf16_f32 v178, v86, v87
	v_add_f32_e32 v186, v186, v88
	v_add_f32_e32 v187, v187, v89
	v_cvt_pk_bf16_f32 v179, v88, v89
	s_waitcnt lgkmcnt(7)
	v_mfma_f32_32x32x16_bf16 v[50:65], v[114:117], v[98:101], 0
	ds_read_b128 v[114:117], v224 offset:49152
	v_exp_f32_e32 v90, v90
	v_exp_f32_e32 v91, v91
	v_exp_f32_e32 v92, v92
	s_waitcnt lgkmcnt(7)
	v_mfma_f32_32x32x16_bf16 v[50:65], v[118:121], v[102:105], v[50:65]
	ds_read_b128 v[118:121], v225 offset:49152
	v_exp_f32_e32 v93, v93
	v_cvt_pk_bf16_f32 v180, v90, v91
	v_add_f32_e32 v184, v184, v90
	v_add_f32_e32 v185, v185, v91
	v_exp_f32_e32 v94, v94
	s_waitcnt lgkmcnt(7)
	v_mfma_f32_32x32x16_bf16 v[50:65], v[122:125], v[106:109], v[50:65]
	ds_read_b128 v[122:125], v226 offset:49152
	v_exp_f32_e32 v95, v95
	v_cvt_pk_bf16_f32 v181, v92, v93
	v_add_f32_e32 v186, v186, v92
	v_add_f32_e32 v187, v187, v93
	v_exp_f32_e32 v96, v96
	s_waitcnt lgkmcnt(7)
	v_mfma_f32_32x32x16_bf16 v[50:65], v[126:129], v[110:113], v[50:65]
	ds_read_b128 v[126:129], v227 offset:49152
	v_exp_f32_e32 v97, v97
	v_add_f32_e32 v184, v184, v94
	v_add_f32_e32 v185, v185, v95
	v_cvt_pk_bf16_f32 v182, v94, v95
	v_add_f32_e32 v186, v186, v96
	v_add_f32_e32 v187, v187, v97
	v_cvt_pk_bf16_f32 v183, v96, v97
	s_waitcnt lgkmcnt(7)
	v_mfma_f32_32x32x16_bf16 v[18:33], v[152:155], v[176:179], v[18:33]
	ds_read_b128 v[152:155], v224 offset:40960
	v_exp_f32_e32 v34, v34
	v_exp_f32_e32 v35, v35
	v_exp_f32_e32 v36, v36
	s_waitcnt lgkmcnt(7)
	v_mfma_f32_32x32x16_bf16 v[2:17], v[156:159], v[176:179], v[2:17]
	ds_read_b128 v[156:159], v224 offset:45056
	v_exp_f32_e32 v37, v37
	v_cvt_pk_bf16_f32 v168, v34, v35
	v_add_f32_e32 v184, v184, v34
	v_add_f32_e32 v185, v185, v35
	v_exp_f32_e32 v38, v38
	s_waitcnt lgkmcnt(7)
; DI f32x16 mfma32(bf16x8 a, bf16x8 b, f32x16 c) { return __builtin_amdgcn_mfma_f32_32x32x16_bf16(a, b, c, 0, 0, 0); }
; DI float fast_exp2(float x) { return __builtin_amdgcn_exp2f(x); }
; #define ATT_WRITE2(HALF, H) do { _Pragma("unroll") for (int j_ = 0; j_ < 2; ++j_) { \
;       char* sl_ = lds + (HALF) * 65536 + (2 * (H) + j_) * 16384; \
;       *(u32x4*)(sl_ + woff) = rk[j_]; \
;       *(u32x4*)(sl_ + 8192 + woff) = rv[j_]; } } while (0)
; template <bool NA, bool TRACK>
; DI void attn_item(char* lds, const bf16_t* P, bf16_t* Y, const bf16_t* vt, int rp, int q_off, int k1_off, int nt1,
;                   int vk1, int k2_off, int nt2, int vk2, int g_off, int y_off, int rlo, const float* rpb) {
;     ...
;       const bool more = it + 1 < niter;
;       if (more) ATT_LOAD2(it + 1, 0);
;       const char* Kb = lds + hb * 65536;
;       f32x16 sc[2], sn[2];
;     ...
;       ATT_QK(sc, 0);
; #pragma unroll
;       for (int j = 0; j < TPI; ++j) {
;         const char* Vs = Kb + j * 16384 + 8192;
;         if (j + 1 < TPI) ATT_QK(sn, j + 1);
;         float ps = 0.f;
; #pragma unroll
;         for (int kt = 0; kt < 2; ++kt) {
;           bf16x8 vf[4];
; #pragma unroll
;           for (int sp = 0; sp < 2; ++sp)
; #pragma unroll
;             for (int dm = 0; dm < 2; ++dm)
;               vf[sp * 2 + dm] = *(const bf16x8*)(Vs + (dm * 32 + r) * 128 + (((4 * kt + 2 * sp + h) ^ swz) << 4));
; #pragma unroll
;           for (int i = 0; i < 16; ++i) {
;             const float pv = fast_exp2(sc[kt][i]);
;             ps += pv;
;             sc[kt][i] = pv;
;           }
; #pragma unroll
;           for (int sp = 0; sp < 2; ++sp) {
;             u32x4 pu;
;             pu[0] = pk2(sc[kt][8 * sp + 0], sc[kt][8 * sp + 1]);
;             pu[1] = pk2(sc[kt][8 * sp + 2], sc[kt][8 * sp + 3]);
;             pu[2] = pk2(sc[kt][8 * sp + 4], sc[kt][8 * sp + 5]);
;             pu[3] = pk2(sc[kt][8 * sp + 6], sc[kt][8 * sp + 7]);
;             const bf16x8 pf = __builtin_bit_cast(bf16x8, pu);
; #pragma unroll
;             for (int dm = 0; dm < 2; ++dm) o[dm] = mfma32(vf[sp * 2 + dm], pf, o[dm]);
;           }
;         }
;         l_run += ps;
;         if (j + 1 < TPI) { sc[0] = sn[0]; sc[1] = sn[1]; }
;         if (j == 1 && more) { ATT_WRITE2(hb ^ 1, 0); ATT_LOAD2(it + 1, 1); }
;       }
;       if (more) ATT_WRITE2(hb ^ 1, 1);
	v_mfma_f32_32x32x16_bf16 v[18:33], v[160:163], v[180:183], v[18:33]
	ds_read_b128 v[160:163], v225 offset:40960
	v_exp_f32_e32 v39, v39
	v_cvt_pk_bf16_f32 v169, v36, v37
	v_add_f32_e32 v186, v186, v36
	v_add_f32_e32 v187, v187, v37
	v_exp_f32_e32 v40, v40
	s_waitcnt lgkmcnt(7)
	v_mfma_f32_32x32x16_bf16 v[2:17], v[164:167], v[180:183], v[2:17]
	ds_read_b128 v[164:167], v225 offset:45056
	v_exp_f32_e32 v41, v41
	v_add_f32_e32 v184, v184, v38
	v_add_f32_e32 v185, v185, v39
	v_cvt_pk_bf16_f32 v170, v38, v39
	v_add_f32_e32 v186, v186, v40
	v_add_f32_e32 v187, v187, v41
	v_cvt_pk_bf16_f32 v171, v40, v41
	s_waitcnt lgkmcnt(7)
	v_mfma_f32_32x32x16_bf16 v[66:81], v[114:117], v[98:101], 0
	ds_read_b128 v[114:117], v224 offset:53248
	v_exp_f32_e32 v42, v42
	v_exp_f32_e32 v43, v43
	v_exp_f32_e32 v44, v44
	s_waitcnt lgkmcnt(7)
	v_mfma_f32_32x32x16_bf16 v[66:81], v[118:121], v[102:105], v[66:81]
	ds_read_b128 v[118:121], v225 offset:53248
	s_waitcnt vmcnt(7)
	ds_write_b128 v139, v[192:195]
	v_exp_f32_e32 v45, v45
	v_cvt_pk_bf16_f32 v172, v42, v43
	v_add_f32_e32 v184, v184, v42
	v_add_f32_e32 v185, v185, v43
	v_exp_f32_e32 v46, v46
	s_waitcnt lgkmcnt(8)
	v_mfma_f32_32x32x16_bf16 v[66:81], v[122:125], v[106:109], v[66:81]
	ds_read_b128 v[122:125], v226 offset:53248
	v_exp_f32_e32 v47, v47
	v_cvt_pk_bf16_f32 v173, v44, v45
	v_add_f32_e32 v186, v186, v44
	v_add_f32_e32 v187, v187, v45
	v_exp_f32_e32 v48, v48
	s_waitcnt lgkmcnt(8)
	v_mfma_f32_32x32x16_bf16 v[66:81], v[126:129], v[110:113], v[66:81]
	ds_read_b128 v[126:129], v227 offset:53248
	v_exp_f32_e32 v49, v49
	v_add_f32_e32 v184, v184, v46
	v_add_f32_e32 v185, v185, v47
	v_cvt_pk_bf16_f32 v174, v46, v47
	v_add_f32_e32 v186, v186, v48
	v_add_f32_e32 v187, v187, v49
	v_cvt_pk_bf16_f32 v175, v48, v49
	s_waitcnt lgkmcnt(8)
	v_mfma_f32_32x32x16_bf16 v[18:33], v[152:155], v[168:171], v[18:33]
	ds_read_b128 v[152:155], v226 offset:40960
	v_exp_f32_e32 v50, v50
	v_exp_f32_e32 v51, v51
	v_exp_f32_e32 v52, v52
	s_waitcnt lgkmcnt(8)
	v_mfma_f32_32x32x16_bf16 v[2:17], v[156:159], v[168:171], v[2:17]
	ds_read_b128 v[156:159], v226 offset:45056
	s_waitcnt vmcnt(6)
	ds_write_b128 v139, v[196:199] offset:8192
	v_exp_f32_e32 v53, v53
	v_cvt_pk_bf16_f32 v176, v50, v51
	v_add_f32_e32 v184, v184, v50
	v_add_f32_e32 v185, v185, v51
	v_exp_f32_e32 v54, v54
	s_waitcnt lgkmcnt(9)
	v_mfma_f32_32x32x16_bf16 v[18:33], v[160:163], v[172:175], v[18:33]
	ds_read_b128 v[160:163], v227 offset:40960
	v_exp_f32_e32 v55, v55
	v_cvt_pk_bf16_f32 v177, v52, v53
	v_add_f32_e32 v186, v186, v52
	v_add_f32_e32 v187, v187, v53
	v_exp_f32_e32 v56, v56
	s_waitcnt lgkmcnt(9)
	v_mfma_f32_32x32x16_bf16 v[2:17], v[164:167], v[172:175], v[2:17]
	ds_read_b128 v[164:167], v227 offset:45056
	v_exp_f32_e32 v57, v57
	v_add_f32_e32 v184, v184, v54
	v_add_f32_e32 v185, v185, v55
	v_cvt_pk_bf16_f32 v178, v54, v55
	v_add_f32_e32 v186, v186, v56
	v_add_f32_e32 v187, v187, v57
	v_cvt_pk_bf16_f32 v179, v56, v57
	s_waitcnt lgkmcnt(9)
	v_mfma_f32_32x32x16_bf16 v[82:97], v[114:117], v[98:101], 0
	v_exp_f32_e32 v58, v58
	v_exp_f32_e32 v59, v59
	v_exp_f32_e32 v60, v60
	s_waitcnt lgkmcnt(8)
	v_mfma_f32_32x32x16_bf16 v[82:97], v[118:121], v[102:105], v[82:97]
	s_waitcnt vmcnt(5)
	ds_write_b128 v139, v[200:203] offset:16384
	v_exp_f32_e32 v61, v61
	v_cvt_pk_bf16_f32 v180, v58, v59
	v_add_f32_e32 v184, v184, v58
	v_add_f32_e32 v185, v185, v59
	v_exp_f32_e32 v62, v62
	s_waitcnt lgkmcnt(7)
	v_mfma_f32_32x32x16_bf16 v[82:97], v[122:125], v[106:109], v[82:97]
	v_exp_f32_e32 v63, v63
	v_cvt_pk_bf16_f32 v181, v60, v61
	v_add_f32_e32 v186, v186, v60
	v_add_f32_e32 v187, v187, v61
	v_exp_f32_e32 v64, v64
	s_waitcnt lgkmcnt(6)
	v_mfma_f32_32x32x16_bf16 v[82:97], v[126:129], v[110:113], v[82:97]
	v_exp_f32_e32 v65, v65
	v_add_f32_e32 v184, v184, v62
	v_add_f32_e32 v185, v185, v63
	v_cvt_pk_bf16_f32 v182, v62, v63
	v_add_f32_e32 v186, v186, v64
	v_add_f32_e32 v187, v187, v65
	v_cvt_pk_bf16_f32 v183, v64, v65
	s_waitcnt lgkmcnt(5)
	v_mfma_f32_32x32x16_bf16 v[18:33], v[152:155], v[176:179], v[18:33]
	ds_read_b128 v[152:155], v224 offset:57344
	v_exp_f32_e32 v66, v66
	v_exp_f32_e32 v67, v67
	v_exp_f32_e32 v68, v68
	s_waitcnt lgkmcnt(5)
	v_mfma_f32_32x32x16_bf16 v[2:17], v[156:159], v[176:179], v[2:17]
	ds_read_b128 v[156:159], v224 offset:61440
	s_waitcnt vmcnt(4)
	ds_write_b128 v139, v[204:207] offset:24576
	v_exp_f32_e32 v69, v69
	v_cvt_pk_bf16_f32 v168, v66, v67
	v_add_f32_e32 v184, v184, v66
	v_add_f32_e32 v185, v185, v67
	v_exp_f32_e32 v70, v70
	s_waitcnt lgkmcnt(5)
	v_mfma_f32_32x32x16_bf16 v[18:33], v[160:163], v[180:183], v[18:33]
	ds_read_b128 v[160:163], v225 offset:57344
	v_exp_f32_e32 v71, v71
	v_cvt_pk_bf16_f32 v169, v68, v69
	v_add_f32_e32 v186, v186, v68
	v_add_f32_e32 v187, v187, v69
	v_exp_f32_e32 v72, v72
	s_waitcnt lgkmcnt(5)
	v_mfma_f32_32x32x16_bf16 v[2:17], v[164:167], v[180:183], v[2:17]
	ds_read_b128 v[164:167], v225 offset:61440
	v_exp_f32_e32 v73, v73
	v_add_f32_e32 v184, v184, v70
	v_add_f32_e32 v185, v185, v71
	v_cvt_pk_bf16_f32 v170, v70, v71
	v_add_f32_e32 v186, v186, v72
	v_add_f32_e32 v187, v187, v73
	v_cvt_pk_bf16_f32 v171, v72, v73
	v_exp_f32_e32 v74, v74
	v_exp_f32_e32 v75, v75
	v_exp_f32_e32 v76, v76
	s_waitcnt lgkmcnt(4)
	v_mfma_f32_32x32x16_bf16 v[18:33], v[152:155], v[168:171], v[18:33]
	ds_read_b128 v[152:155], v226 offset:57344
	s_waitcnt vmcnt(3)
	ds_write_b128 v139, v[208:211] offset:32768
	v_exp_f32_e32 v77, v77
	v_cvt_pk_bf16_f32 v172, v74, v75
	v_add_f32_e32 v184, v184, v74
	v_add_f32_e32 v185, v185, v75
	v_exp_f32_e32 v78, v78
	s_waitcnt lgkmcnt(5)
	v_mfma_f32_32x32x16_bf16 v[2:17], v[156:159], v[168:171], v[2:17]
	ds_read_b128 v[156:159], v226 offset:61440
	s_waitcnt vmcnt(2)
; DI f32x16 mfma32(bf16x8 a, bf16x8 b, f32x16 c) { return __builtin_amdgcn_mfma_f32_32x32x16_bf16(a, b, c, 0, 0, 0); }
; DI float fast_exp2(float x) { return __builtin_amdgcn_exp2f(x); }
; #define ATT_WRITE2(HALF, H) do { _Pragma("unroll") for (int j_ = 0; j_ < 2; ++j_) { \
;       char* sl_ = lds + (HALF) * 65536 + (2 * (H) + j_) * 16384; \
;       *(u32x4*)(sl_ + woff) = rk[j_]; \
;       *(u32x4*)(sl_ + 8192 + woff) = rv[j_]; } } while (0)
; template <bool NA, bool TRACK>
; DI void attn_item(char* lds, const bf16_t* P, bf16_t* Y, const bf16_t* vt, int rp, int q_off, int k1_off, int nt1,
;                   int vk1, int k2_off, int nt2, int vk2, int g_off, int y_off, int rlo, const float* rpb) {
;     ...
; #pragma unroll
;             for (int dm = 0; dm < 2; ++dm)
;               vf[sp * 2 + dm] = *(const bf16x8*)(Vs + (dm * 32 + r) * 128 + (((4 * kt + 2 * sp + h) ^ swz) << 4));
; #pragma unroll
;           for (int i = 0; i < 16; ++i) {
;             const float pv = fast_exp2(sc[kt][i]);
;             ps += pv;
;             sc[kt][i] = pv;
;           }
; #pragma unroll
;           for (int sp = 0; sp < 2; ++sp) {
;             u32x4 pu;
;             pu[0] = pk2(sc[kt][8 * sp + 0], sc[kt][8 * sp + 1]);
;             pu[1] = pk2(sc[kt][8 * sp + 2], sc[kt][8 * sp + 3]);
;             pu[2] = pk2(sc[kt][8 * sp + 4], sc[kt][8 * sp + 5]);
;             pu[3] = pk2(sc[kt][8 * sp + 6], sc[kt][8 * sp + 7]);
;             const bf16x8 pf = __builtin_bit_cast(bf16x8, pu);
; #pragma unroll
;             for (int dm = 0; dm < 2; ++dm) o[dm] = mfma32(vf[sp * 2 + dm], pf, o[dm]);
;           }
;         }
;         l_run += ps;
;         if (j + 1 < TPI) { sc[0] = sn[0]; sc[1] = sn[1]; }
;         if (j == 1 && more) { ATT_WRITE2(hb ^ 1, 0); ATT_LOAD2(it + 1, 1); }
;       }
;       if (more) ATT_WRITE2(hb ^ 1, 1);
	ds_write_b128 v139, v[212:215] offset:40960
	v_exp_f32_e32 v79, v79
	v_cvt_pk_bf16_f32 v173, v76, v77
	v_add_f32_e32 v186, v186, v76
	v_add_f32_e32 v187, v187, v77
	v_exp_f32_e32 v80, v80
	v_exp_f32_e32 v81, v81
	v_add_f32_e32 v184, v184, v78
	v_add_f32_e32 v185, v185, v79
	v_cvt_pk_bf16_f32 v174, v78, v79
	v_add_f32_e32 v186, v186, v80
	v_add_f32_e32 v187, v187, v81
	v_cvt_pk_bf16_f32 v175, v80, v81
	s_waitcnt lgkmcnt(5)
	v_mfma_f32_32x32x16_bf16 v[18:33], v[160:163], v[172:175], v[18:33]
	ds_read_b128 v[160:163], v227 offset:57344
	s_waitcnt vmcnt(1)
	ds_write_b128 v139, v[216:219] offset:49152
	v_exp_f32_e32 v82, v82
	v_exp_f32_e32 v83, v83
	v_exp_f32_e32 v84, v84
	s_waitcnt lgkmcnt(6)
	v_mfma_f32_32x32x16_bf16 v[2:17], v[164:167], v[172:175], v[2:17]
	ds_read_b128 v[164:167], v227 offset:61440
	s_waitcnt vmcnt(0)
	ds_write_b128 v139, v[220:223] offset:57344
	v_exp_f32_e32 v85, v85
	v_cvt_pk_bf16_f32 v176, v82, v83
	v_add_f32_e32 v184, v184, v82
	v_add_f32_e32 v185, v185, v83
	v_exp_f32_e32 v86, v86
	v_exp_f32_e32 v87, v87
	v_cvt_pk_bf16_f32 v177, v84, v85
	v_add_f32_e32 v186, v186, v84
	v_add_f32_e32 v187, v187, v85
	v_exp_f32_e32 v88, v88
	v_exp_f32_e32 v89, v89
	v_add_f32_e32 v184, v184, v86
	v_add_f32_e32 v185, v185, v87
	v_cvt_pk_bf16_f32 v178, v86, v87
	v_add_f32_e32 v186, v186, v88
	v_add_f32_e32 v187, v187, v89
	v_cvt_pk_bf16_f32 v179, v88, v89
	s_waitcnt lgkmcnt(7)
	v_mfma_f32_32x32x16_bf16 v[18:33], v[152:155], v[176:179], v[18:33]
	v_exp_f32_e32 v90, v90
	v_exp_f32_e32 v91, v91
	v_exp_f32_e32 v92, v92
	v_exp_f32_e32 v93, v93
	v_cvt_pk_bf16_f32 v180, v90, v91
	v_add_f32_e32 v184, v184, v90
	v_add_f32_e32 v185, v185, v91
	v_exp_f32_e32 v94, v94
	s_waitcnt lgkmcnt(5)
	v_mfma_f32_32x32x16_bf16 v[2:17], v[156:159], v[176:179], v[2:17]
	v_exp_f32_e32 v95, v95
	v_cvt_pk_bf16_f32 v181, v92, v93
	v_add_f32_e32 v186, v186, v92
	v_add_f32_e32 v187, v187, v93
	v_exp_f32_e32 v96, v96
	v_exp_f32_e32 v97, v97
	v_add_f32_e32 v184, v184, v94
	v_add_f32_e32 v185, v185, v95
	v_cvt_pk_bf16_f32 v182, v94, v95
	v_add_f32_e32 v186, v186, v96
	v_add_f32_e32 v187, v187, v97
	v_cvt_pk_bf16_f32 v183, v96, v97
	s_waitcnt lgkmcnt(3)
	v_mfma_f32_32x32x16_bf16 v[18:33], v[160:163], v[180:183], v[18:33]
	s_waitcnt lgkmcnt(1)
	v_mfma_f32_32x32x16_bf16 v[2:17], v[164:167], v[180:183], v[2:17]
	s_waitcnt lgkmcnt(0)
	s_barrier
	v_xor_b32_e32 v224, 0x10000, v224
	v_xor_b32_e32 v225, 0x10000, v225
	v_xor_b32_e32 v226, 0x10000, v226
	v_xor_b32_e32 v227, 0x10000, v227
	v_xor_b32_e32 v139, 0x10000, v139
	s_add_i32 s18, s18, 1
	s_cmp_lt_i32 s18, s19
	s_cbranch_scc1 .Ldn_loop
; DI float bflo(unsigned u) { return __uint_as_float(u << 16); }
; DI float bfhi(unsigned u) { return __uint_as_float(u & 0xffff0000u); }
; template <bool NA, bool TRACK>
; DI void attn_item(char* lds, const bf16_t* P, bf16_t* Y, const bf16_t* vt, int rp, int q_off, int k1_off, int nt1,
;                   int vk1, int k2_off, int nt2, int vk2, int g_off, int y_off, int rlo, const float* rpb) {
;     ...
;   const float lt = l_run + __shfl_xor(l_run, 32);
;   const float inv = 1.f / lt;
;   int row = w * 32 + r;
;   asm volatile("" : "+v"(row));
;   bf16_t* yp = Y + y_off;
; #pragma unroll
;   for (int dm = 0; dm < 2; ++dm) {
;     u32x2 ov[4];
; #pragma unroll
;     for (int g = 0; g < 4; ++g) {
;       const u32x2 gv = gate[dm][g];
;       ov[g][0] = pk2(o[dm][4 * g + 0] * inv * bflo(gv[0]), o[dm][4 * g + 1] * inv * bfhi(gv[0]));
;       ov[g][1] = pk2(o[dm][4 * g + 2] * inv * bflo(gv[1]), o[dm][4 * g + 3] * inv * bfhi(gv[1]));
;     }
; #pragma unroll
;     for (int a = 0; a < 2; ++a) {
;       const int ga = 2 * a, gb = 2 * a + 1;
;       const unsigned s0 = h ? ov[ga][0] : ov[gb][0], s1 = h ? ov[ga][1] : ov[gb][1];
;       const unsigned r0 = (unsigned)__shfl_xor((int)s0, 32), r1 = (unsigned)__shfl_xor((int)s1, 32);
;       u32x4 wv;
;       wv[0] = h ? r0 : ov[ga][0];
;       wv[1] = h ? r1 : ov[ga][1];
;       wv[2] = h ? ov[gb][0] : r0;
;       wv[3] = h ? ov[gb][1] : r1;
;       *(u32x4*)(yp + (size_t)row * DM + dm * 32 + 8 * (ga + h)) = wv;
;     }
;   }
	v_add_f32_e32 v184, v184, v185
	v_add_f32_e32 v186, v186, v187
	s_nop 0
	v_add_f32_e32 v160, v184, v186
	ds_bpermute_b32 v0, v190, v160
	v_readlane_b32 s36, v254, 41
	v_ashrrev_i32_e32 v151, 31, v150
	v_readlane_b32 s50, v254, 55
	s_waitcnt lgkmcnt(0)
	v_add_f32_e32 v0, v160, v0
	v_div_scale_f32 v34, s[2:3], v0, v0, 1.0
	v_rcp_f32_e32 v35, v34
	v_readlane_b32 s51, v254, 56
	v_readlane_b32 s37, v254, 42
	v_readlane_b32 s38, v254, 43
	v_fma_f32 v36, -v34, v35, 1.0
	v_fmac_f32_e32 v35, v36, v35
	v_div_scale_f32 v36, vcc, 1.0, v0, 1.0
	v_mul_f32_e32 v37, v36, v35
	v_fma_f32 v38, -v34, v37, v36
	v_fmac_f32_e32 v37, v38, v35
	v_fma_f32 v34, -v34, v37, v36
	v_div_fmas_f32 v34, v34, v35, v37
	v_cmp_eq_u32_e32 vcc, 0, v147
	v_ashrrev_i32_e32 v147, 31, v146
	v_div_fixup_f32 v34, v34, v0, 1.0
	v_lshl_add_u64 v[36:37], v[150:151], 1, s[50:51]
	v_lshlrev_b64 v[38:39], 11, v[146:147]
	v_lshl_add_u64 v[36:37], v[36:37], 0, v[38:39]
	v_pk_mul_f32 v[18:19], v[18:19], v[34:35] op_sel_hi:[1,0]
	v_lshlrev_b32_e32 v38, 16, v148
	v_and_b32_e32 v39, 0xffff0000, v148
	v_pk_mul_f32 v[18:19], v[18:19], v[38:39]
	v_readlane_b32 s39, v254, 44
	v_cvt_pk_bf16_f32 v0, v18, v19
	v_pk_mul_f32 v[18:19], v[20:21], v[34:35] op_sel_hi:[1,0]
	v_lshlrev_b32_e32 v20, 16, v149
	v_and_b32_e32 v21, 0xffff0000, v149
	v_pk_mul_f32 v[18:19], v[18:19], v[20:21]
	v_lshlrev_b32_e32 v20, 16, v144
	v_cvt_pk_bf16_f32 v35, v18, v19
	v_pk_mul_f32 v[18:19], v[22:23], v[34:35] op_sel_hi:[1,0]
	v_and_b32_e32 v21, 0xffff0000, v144
	v_pk_mul_f32 v[18:19], v[18:19], v[20:21]
	v_lshlrev_b32_e32 v20, 16, v145
	v_cvt_pk_bf16_f32 v22, v18, v19
	v_pk_mul_f32 v[18:19], v[24:25], v[34:35] op_sel_hi:[1,0]
	v_and_b32_e32 v21, 0xffff0000, v145
	v_pk_mul_f32 v[18:19], v[18:19], v[20:21]
	v_lshlrev_b32_e32 v20, 16, v142
	v_cvt_pk_bf16_f32 v23, v18, v19
	v_pk_mul_f32 v[18:19], v[26:27], v[34:35] op_sel_hi:[1,0]
	v_and_b32_e32 v21, 0xffff0000, v142
	v_pk_mul_f32 v[18:19], v[18:19], v[20:21]
	v_lshlrev_b32_e32 v20, 16, v143
	v_cvt_pk_bf16_f32 v24, v18, v19
	v_pk_mul_f32 v[18:19], v[28:29], v[34:35] op_sel_hi:[1,0]
	v_and_b32_e32 v21, 0xffff0000, v143
	v_pk_mul_f32 v[18:19], v[18:19], v[20:21]
	v_lshlrev_b32_e32 v20, 16, v140
	v_cvt_pk_bf16_f32 v25, v18, v19
	v_pk_mul_f32 v[18:19], v[30:31], v[34:35] op_sel_hi:[1,0]
	v_and_b32_e32 v21, 0xffff0000, v140
	v_pk_mul_f32 v[18:19], v[18:19], v[20:21]
	v_lshlrev_b32_e32 v20, 16, v141
	v_cvt_pk_bf16_f32 v26, v18, v19
	v_pk_mul_f32 v[18:19], v[32:33], v[34:35] op_sel_hi:[1,0]
	v_and_b32_e32 v21, 0xffff0000, v141
	v_pk_mul_f32 v[18:19], v[18:19], v[20:21]
	v_pk_mul_f32 v[2:3], v[2:3], v[34:35] op_sel_hi:[1,0]
	v_cvt_pk_bf16_f32 v27, v18, v19
	v_cndmask_b32_e32 v18, v0, v22, vcc
	v_cndmask_b32_e32 v19, v35, v23, vcc
	ds_bpermute_b32 v20, v190, v18
	ds_bpermute_b32 v21, v190, v19
	v_readlane_b32 s40, v254, 45
	v_readlane_b32 s41, v254, 46
	v_readlane_b32 s42, v254, 47
	s_waitcnt lgkmcnt(1)
	v_cndmask_b32_e32 v18, v20, v0, vcc
	v_lshlrev_b32_e32 v0, 1, v138
	s_waitcnt lgkmcnt(0)
	v_cndmask_b32_e32 v19, v21, v35, vcc
	v_cndmask_b32_e32 v20, v22, v20, vcc
	v_cndmask_b32_e32 v21, v23, v21, vcc
	v_lshl_add_u64 v[22:23], v[36:37], 0, v[0:1]
	global_store_dwordx4 v[22:23], v[18:21], off
	v_cndmask_b32_e32 v0, v24, v26, vcc
	ds_bpermute_b32 v0, v190, v0
	v_cndmask_b32_e32 v18, v25, v27, vcc
	ds_bpermute_b32 v21, v190, v18
	v_readlane_b32 s43, v254, 48
	v_readlane_b32 s44, v254, 49
	s_waitcnt lgkmcnt(1)
	v_cndmask_b32_e32 v18, v0, v24, vcc
	v_cndmask_b32_e32 v20, v26, v0, vcc
	s_waitcnt lgkmcnt(0)
	v_cndmask_b32_e32 v19, v21, v25, vcc
	v_cndmask_b32_e32 v21, v27, v21, vcc
	global_store_dwordx4 v[22:23], v[18:21], off offset:32
	v_readlane_b32 s45, v254, 50
	v_readlane_b32 s46, v254, 51
	v_lshlrev_b32_e32 v18, 16, v136
	v_and_b32_e32 v19, 0xffff0000, v136
	v_pk_mul_f32 v[2:3], v[2:3], v[18:19]
	v_readlane_b32 s47, v254, 52
	v_cvt_pk_bf16_f32 v0, v2, v3
	v_pk_mul_f32 v[2:3], v[4:5], v[34:35] op_sel_hi:[1,0]
	v_lshlrev_b32_e32 v4, 16, v137
	v_and_b32_e32 v5, 0xffff0000, v137
	v_pk_mul_f32 v[2:3], v[2:3], v[4:5]
	v_lshlrev_b32_e32 v4, 16, v134
	v_cvt_pk_bf16_f32 v18, v2, v3
	v_pk_mul_f32 v[2:3], v[6:7], v[34:35] op_sel_hi:[1,0]
	v_and_b32_e32 v5, 0xffff0000, v134
	v_pk_mul_f32 v[2:3], v[2:3], v[4:5]
	v_lshlrev_b32_e32 v4, 16, v135
	v_cvt_pk_bf16_f32 v6, v2, v3
	v_pk_mul_f32 v[2:3], v[8:9], v[34:35] op_sel_hi:[1,0]
	v_and_b32_e32 v5, 0xffff0000, v135
	v_pk_mul_f32 v[2:3], v[2:3], v[4:5]
	v_lshlrev_b32_e32 v4, 16, v132
	v_cvt_pk_bf16_f32 v7, v2, v3
	v_pk_mul_f32 v[2:3], v[10:11], v[34:35] op_sel_hi:[1,0]
	v_and_b32_e32 v5, 0xffff0000, v132
	v_pk_mul_f32 v[2:3], v[2:3], v[4:5]
	v_lshlrev_b32_e32 v4, 16, v133
	v_cvt_pk_bf16_f32 v8, v2, v3
	v_pk_mul_f32 v[2:3], v[12:13], v[34:35] op_sel_hi:[1,0]
	v_and_b32_e32 v5, 0xffff0000, v133
	v_pk_mul_f32 v[2:3], v[2:3], v[4:5]
	v_lshlrev_b32_e32 v4, 16, v130
	v_cvt_pk_bf16_f32 v9, v2, v3
	v_pk_mul_f32 v[2:3], v[14:15], v[34:35] op_sel_hi:[1,0]
	v_and_b32_e32 v5, 0xffff0000, v130
	v_pk_mul_f32 v[2:3], v[2:3], v[4:5]
	v_lshlrev_b32_e32 v4, 16, v131
	v_cvt_pk_bf16_f32 v10, v2, v3
	v_pk_mul_f32 v[2:3], v[16:17], v[34:35] op_sel_hi:[1,0]
	v_and_b32_e32 v5, 0xffff0000, v131
	v_pk_mul_f32 v[2:3], v[2:3], v[4:5]
	v_readlane_b32 s48, v254, 53
	v_cvt_pk_bf16_f32 v11, v2, v3
	v_cndmask_b32_e32 v2, v0, v6, vcc
	v_cndmask_b32_e32 v3, v18, v7, vcc
	ds_bpermute_b32 v4, v190, v2
	ds_bpermute_b32 v5, v190, v3
	v_readlane_b32 s49, v254, 54
	s_mov_b64 s[2:3], 0
	s_waitcnt lgkmcnt(1)
	v_cndmask_b32_e32 v2, v4, v0, vcc
	s_waitcnt lgkmcnt(0)
	v_cndmask_b32_e32 v3, v5, v18, vcc
	v_cndmask_b32_e32 v4, v6, v4, vcc
	v_cndmask_b32_e32 v5, v7, v5, vcc
	global_store_dwordx4 v[22:23], v[2:5], off offset:64
	v_cndmask_b32_e32 v0, v8, v10, vcc
	ds_bpermute_b32 v0, v190, v0
	v_cndmask_b32_e32 v2, v9, v11, vcc
	ds_bpermute_b32 v5, v190, v2
	s_waitcnt lgkmcnt(1)
	v_cndmask_b32_e32 v2, v0, v8, vcc
	v_cndmask_b32_e32 v4, v10, v0, vcc
	s_waitcnt lgkmcnt(0)
	v_cndmask_b32_e32 v3, v5, v9, vcc
	v_cndmask_b32_e32 v5, v11, v5, vcc
	global_store_dwordx4 v[22:23], v[2:5], off offset:96
